# stack14: grid barriers 2..9 poll the cross-XCD arrival counter (top >= gen*n_xcds) instead of the separate generation flag
# baseline (speedup 1.0000x reference)
; DI void grid_barrier_xcd(unsigned* bar, const unsigned gen, const unsigned my_xcc, const unsigned n_local, const unsigned n_xcds) {
;     ...
;       const unsigned t = __hip_atomic_fetch_add(top, 1u, __ATOMIC_RELAXED, __HIP_MEMORY_SCOPE_AGENT);
;       if (t + 1u == gen * n_xcds) __hip_atomic_store(rel, gen, __ATOMIC_RELAXED, __HIP_MEMORY_SCOPE_AGENT);
;     }
;     unsigned spins = 0;
;     while (__hip_atomic_load(rel, __ATOMIC_RELAXED, __HIP_MEMORY_SCOPE_AGENT) < gen) {
;       __builtin_amdgcn_s_sleep(1);
;       if (++spins > (1u << 24)) break;
;     }
.LBB0_135:
	s_or_b64 exec, exec, s[12:13]
	v_readfirstlane_b32 s101, v200
	s_mul_i32 s101, s101, s3
	s_add_i32 s101, s101, -1
	s_sub_u32 s10, s10, 0x100
	s_subb_u32 s11, s11, 0
	s_mov_b32 s0, 0x1000000
	v_mov_b32_e32 v1, 0
	s_branch .LBB0_138

; DI void grid_barrier_xcd(unsigned* bar, const unsigned gen, const unsigned my_xcc, const unsigned n_local, const unsigned n_xcds) {
;     ...
;     unsigned spins = 0;
;     while (__hip_atomic_load(rel, __ATOMIC_RELAXED, __HIP_MEMORY_SCOPE_AGENT) < gen) {
;       __builtin_amdgcn_s_sleep(1);
;       if (++spins > (1u << 24)) break;
;     }
.LBB0_138:
	global_load_dword v2, v1, s[10:11] sc1
	s_mov_b64 s[12:13], -1
	s_waitcnt vmcnt(0)
	v_cmp_lt_u32_e32 vcc, s101, v2
	s_cbranch_vccnz .LBB0_137
	s_cmp_lg_u32 s0, 0
	s_sleep 1
	s_cbranch_scc0 .LBB0_136
	global_load_dword v2, v1, s[10:11] sc1
	s_waitcnt vmcnt(0)
	v_cmp_ge_u32_e32 vcc, s101, v2
	s_cbranch_vccz .LBB0_137
	s_sleep 1
	global_load_dword v2, v1, s[10:11] sc1
	s_waitcnt vmcnt(0)
	v_cmp_ge_u32_e32 vcc, s101, v2
	s_cbranch_vccz .LBB0_137
	s_sleep 1
	global_load_dword v2, v1, s[10:11] sc1
	s_waitcnt vmcnt(0)
	v_cmp_ge_u32_e32 vcc, s101, v2
	s_cbranch_vccz .LBB0_137
	s_sleep 1
	global_load_dword v2, v1, s[10:11] sc1
	s_waitcnt vmcnt(0)
	v_cmp_ge_u32_e32 vcc, s101, v2
	s_cbranch_vccz .LBB0_137
	s_sleep 1
	global_load_dword v2, v1, s[10:11] sc1
	s_waitcnt vmcnt(0)
	v_cmp_ge_u32_e32 vcc, s101, v2
	s_cbranch_vccz .LBB0_137
	s_sleep 1
	global_load_dword v2, v1, s[10:11] sc1
	s_waitcnt vmcnt(0)
	v_cmp_ge_u32_e32 vcc, s101, v2
	s_cbranch_vccz .LBB0_137
	s_sleep 1
	global_load_dword v2, v1, s[10:11] sc1
	s_waitcnt vmcnt(0)
	v_cmp_ge_u32_e32 vcc, s101, v2
	s_cbranch_vccz .LBB0_137
	s_sleep 1
	s_add_i32 s0, s0, -8
	s_mov_b64 s[12:13], 0
	s_branch .LBB0_137

; DI void grid_barrier_xcd(unsigned* bar, const unsigned gen, const unsigned my_xcc, const unsigned n_local, const unsigned n_xcds) {
;     ...
;       const unsigned t = __hip_atomic_fetch_add(top, 1u, __ATOMIC_RELAXED, __HIP_MEMORY_SCOPE_AGENT);
;       if (t + 1u == gen * n_xcds) __hip_atomic_store(rel, gen, __ATOMIC_RELAXED, __HIP_MEMORY_SCOPE_AGENT);
;     }
;     unsigned spins = 0;
;     while (__hip_atomic_load(rel, __ATOMIC_RELAXED, __HIP_MEMORY_SCOPE_AGENT) < gen) {
;       __builtin_amdgcn_s_sleep(1);
;       if (++spins > (1u << 24)) break;
;     }
.LBB0_268:
	s_or_b64 exec, exec, s[12:13]
	v_readfirstlane_b32 s101, v200
	s_mul_i32 s101, s101, s4
	s_add_i32 s101, s101, -1
	s_sub_u32 s10, s10, 0x100
	s_subb_u32 s11, s11, 0
	s_mov_b32 s0, 0x1000000
	v_mov_b32_e32 v1, 0
	s_branch .LBB0_271

; DI void grid_barrier_xcd(unsigned* bar, const unsigned gen, const unsigned my_xcc, const unsigned n_local, const unsigned n_xcds) {
;     ...
;       const unsigned t = __hip_atomic_fetch_add(top, 1u, __ATOMIC_RELAXED, __HIP_MEMORY_SCOPE_AGENT);
;       if (t + 1u == gen * n_xcds) __hip_atomic_store(rel, gen, __ATOMIC_RELAXED, __HIP_MEMORY_SCOPE_AGENT);
;     }
;     unsigned spins = 0;
;     while (__hip_atomic_load(rel, __ATOMIC_RELAXED, __HIP_MEMORY_SCOPE_AGENT) < gen) {
;       __builtin_amdgcn_s_sleep(1);
;       if (++spins > (1u << 24)) break;
;     }
.LBB0_329:
	s_or_b64 exec, exec, s[12:13]
	v_readfirstlane_b32 s101, v200
	s_mul_i32 s101, s101, s5
	s_add_i32 s101, s101, -1
	s_sub_u32 s8, s8, 0x100
	s_subb_u32 s9, s9, 0
	s_mov_b32 s0, 0x1000000
	v_mov_b32_e32 v1, 0
	s_branch .LBB0_332

; DI void grid_barrier_xcd(unsigned* bar, const unsigned gen, const unsigned my_xcc, const unsigned n_local, const unsigned n_xcds) {
;     ...
;     unsigned spins = 0;
;     while (__hip_atomic_load(rel, __ATOMIC_RELAXED, __HIP_MEMORY_SCOPE_AGENT) < gen) {
;       __builtin_amdgcn_s_sleep(1);
;       if (++spins > (1u << 24)) break;
;     }
.LBB0_332:
	global_load_dword v2, v1, s[8:9] sc1
	s_mov_b64 s[12:13], -1
	s_waitcnt vmcnt(0)
	v_cmp_lt_u32_e32 vcc, s101, v2
	s_cbranch_vccnz .LBB0_331
	s_cmp_lg_u32 s0, 0
	s_sleep 1
	s_cbranch_scc0 .LBB0_330
	global_load_dword v2, v1, s[8:9] sc1
	s_waitcnt vmcnt(0)
	v_cmp_ge_u32_e32 vcc, s101, v2
	s_cbranch_vccz .LBB0_331
	s_sleep 1
	global_load_dword v2, v1, s[8:9] sc1
	s_waitcnt vmcnt(0)
	v_cmp_ge_u32_e32 vcc, s101, v2
	s_cbranch_vccz .LBB0_331
	s_sleep 1
	global_load_dword v2, v1, s[8:9] sc1
	s_waitcnt vmcnt(0)
	v_cmp_ge_u32_e32 vcc, s101, v2
	s_cbranch_vccz .LBB0_331
	s_sleep 1
	global_load_dword v2, v1, s[8:9] sc1
	s_waitcnt vmcnt(0)
	v_cmp_ge_u32_e32 vcc, s101, v2
	s_cbranch_vccz .LBB0_331
	s_sleep 1
	global_load_dword v2, v1, s[8:9] sc1
	s_waitcnt vmcnt(0)
	v_cmp_ge_u32_e32 vcc, s101, v2
	s_cbranch_vccz .LBB0_331
	s_sleep 1
	global_load_dword v2, v1, s[8:9] sc1
	s_waitcnt vmcnt(0)
	v_cmp_ge_u32_e32 vcc, s101, v2
	s_cbranch_vccz .LBB0_331
	s_sleep 1
	global_load_dword v2, v1, s[8:9] sc1
	s_waitcnt vmcnt(0)
	v_cmp_ge_u32_e32 vcc, s101, v2
	s_cbranch_vccz .LBB0_331
	s_sleep 1
	s_add_i32 s0, s0, -8
	s_mov_b64 s[12:13], 0
	s_branch .LBB0_331

; DI void grid_barrier_xcd(unsigned* bar, const unsigned gen, const unsigned my_xcc, const unsigned n_local, const unsigned n_xcds) {
;     ...
;       const unsigned t = __hip_atomic_fetch_add(top, 1u, __ATOMIC_RELAXED, __HIP_MEMORY_SCOPE_AGENT);
;       if (t + 1u == gen * n_xcds) __hip_atomic_store(rel, gen, __ATOMIC_RELAXED, __HIP_MEMORY_SCOPE_AGENT);
;     }
;     unsigned spins = 0;
;     while (__hip_atomic_load(rel, __ATOMIC_RELAXED, __HIP_MEMORY_SCOPE_AGENT) < gen) {
;       __builtin_amdgcn_s_sleep(1);
;       if (++spins > (1u << 24)) break;
;     }
.LBB0_378:
	s_or_b64 exec, exec, s[12:13]
	v_readfirstlane_b32 s101, v200
	s_mul_i32 s101, s101, s3
	s_add_i32 s101, s101, -1
	s_sub_u32 s8, s8, 0x100
	s_subb_u32 s9, s9, 0
	s_mov_b32 s0, 0x1000000
	v_mov_b32_e32 v1, 0
	s_branch .LBB0_381

; DI void grid_barrier_xcd(unsigned* bar, const unsigned gen, const unsigned my_xcc, const unsigned n_local, const unsigned n_xcds) {
;     ...
;       const unsigned t = __hip_atomic_fetch_add(top, 1u, __ATOMIC_RELAXED, __HIP_MEMORY_SCOPE_AGENT);
;       if (t + 1u == gen * n_xcds) __hip_atomic_store(rel, gen, __ATOMIC_RELAXED, __HIP_MEMORY_SCOPE_AGENT);
;     }
;     unsigned spins = 0;
;     while (__hip_atomic_load(rel, __ATOMIC_RELAXED, __HIP_MEMORY_SCOPE_AGENT) < gen) {
;       __builtin_amdgcn_s_sleep(1);
;       if (++spins > (1u << 24)) break;
;     }
.LBB0_487:
	s_or_b64 exec, exec, s[12:13]
	v_readfirstlane_b32 s101, v200
	s_mul_i32 s101, s101, s5
	s_add_i32 s101, s101, -1
	s_sub_u32 s10, s10, 0x100
	s_subb_u32 s11, s11, 0
	s_mov_b32 s0, 0x1000000
	v_mov_b32_e32 v2, 0
	s_branch .LBB0_490

; DI void grid_barrier_xcd(unsigned* bar, const unsigned gen, const unsigned my_xcc, const unsigned n_local, const unsigned n_xcds) {
;     ...
;     unsigned spins = 0;
;     while (__hip_atomic_load(rel, __ATOMIC_RELAXED, __HIP_MEMORY_SCOPE_AGENT) < gen) {
;       __builtin_amdgcn_s_sleep(1);
;       if (++spins > (1u << 24)) break;
;     }
.LBB0_490:
	global_load_dword v3, v2, s[10:11] sc1
	s_mov_b64 s[12:13], -1
	s_waitcnt vmcnt(0)
	v_cmp_lt_u32_e32 vcc, s101, v3
	s_cbranch_vccnz .LBB0_489
	s_cmp_lg_u32 s0, 0
	s_sleep 1
	s_cbranch_scc0 .LBB0_488
	global_load_dword v3, v2, s[10:11] sc1
	s_waitcnt vmcnt(0)
	v_cmp_ge_u32_e32 vcc, s101, v3
	s_cbranch_vccz .LBB0_489
	s_sleep 1
	global_load_dword v3, v2, s[10:11] sc1
	s_waitcnt vmcnt(0)
	v_cmp_ge_u32_e32 vcc, s101, v3
	s_cbranch_vccz .LBB0_489
	s_sleep 1
	global_load_dword v3, v2, s[10:11] sc1
	s_waitcnt vmcnt(0)
	v_cmp_ge_u32_e32 vcc, s101, v3
	s_cbranch_vccz .LBB0_489
	s_sleep 1
	global_load_dword v3, v2, s[10:11] sc1
	s_waitcnt vmcnt(0)
	v_cmp_ge_u32_e32 vcc, s101, v3
	s_cbranch_vccz .LBB0_489
	s_sleep 1
	global_load_dword v3, v2, s[10:11] sc1
	s_waitcnt vmcnt(0)
	v_cmp_ge_u32_e32 vcc, s101, v3
	s_cbranch_vccz .LBB0_489
	s_sleep 1
	global_load_dword v3, v2, s[10:11] sc1
	s_waitcnt vmcnt(0)
	v_cmp_ge_u32_e32 vcc, s101, v3
	s_cbranch_vccz .LBB0_489
	s_sleep 1
	global_load_dword v3, v2, s[10:11] sc1
	s_waitcnt vmcnt(0)
	v_cmp_ge_u32_e32 vcc, s101, v3
	s_cbranch_vccz .LBB0_489
	s_sleep 1
	s_add_i32 s0, s0, -8
	s_mov_b64 s[12:13], 0
	s_branch .LBB0_489

; DI void grid_barrier_xcd(unsigned* bar, const unsigned gen, const unsigned my_xcc, const unsigned n_local, const unsigned n_xcds) {
;     ...
;       const unsigned t = __hip_atomic_fetch_add(top, 1u, __ATOMIC_RELAXED, __HIP_MEMORY_SCOPE_AGENT);
;       if (t + 1u == gen * n_xcds) __hip_atomic_store(rel, gen, __ATOMIC_RELAXED, __HIP_MEMORY_SCOPE_AGENT);
;     }
;     unsigned spins = 0;
;     while (__hip_atomic_load(rel, __ATOMIC_RELAXED, __HIP_MEMORY_SCOPE_AGENT) < gen) {
;       __builtin_amdgcn_s_sleep(1);
;       if (++spins > (1u << 24)) break;
;     }
.LBB0_549:
	s_or_b64 exec, exec, s[12:13]
	v_readfirstlane_b32 s101, v200
	s_mul_i32 s101, s101, s3
	s_add_i32 s101, s101, -1
	s_sub_u32 s10, s10, 0x100
	s_subb_u32 s11, s11, 0
	s_mov_b32 s0, 0x1000000
	v_mov_b32_e32 v2, 0
	s_branch .LBB0_552

; DI void grid_barrier_xcd(unsigned* bar, const unsigned gen, const unsigned my_xcc, const unsigned n_local, const unsigned n_xcds) {
;     ...
;       const unsigned t = __hip_atomic_fetch_add(top, 1u, __ATOMIC_RELAXED, __HIP_MEMORY_SCOPE_AGENT);
;       if (t + 1u == gen * n_xcds) __hip_atomic_store(rel, gen, __ATOMIC_RELAXED, __HIP_MEMORY_SCOPE_AGENT);
;     }
;     unsigned spins = 0;
;     while (__hip_atomic_load(rel, __ATOMIC_RELAXED, __HIP_MEMORY_SCOPE_AGENT) < gen) {
;       __builtin_amdgcn_s_sleep(1);
;       if (++spins > (1u << 24)) break;
;     }
.LBB0_596:
	s_or_b64 exec, exec, s[10:11]
	v_readfirstlane_b32 s101, v200
	s_mul_i32 s101, s101, s0
	s_add_i32 s101, s101, -1
	s_sub_u32 s4, s4, 0x100
	s_subb_u32 s5, s5, 0
	s_mov_b32 s0, 0x1000000
	v_mov_b32_e32 v1, 0
	s_branch .LBB0_599

; DI void grid_barrier_xcd(unsigned* bar, const unsigned gen, const unsigned my_xcc, const unsigned n_local, const unsigned n_xcds) {
;     ...
;     unsigned spins = 0;
;     while (__hip_atomic_load(rel, __ATOMIC_RELAXED, __HIP_MEMORY_SCOPE_AGENT) < gen) {
;       __builtin_amdgcn_s_sleep(1);
;       if (++spins > (1u << 24)) break;
;     }
.LBB0_599:
	global_load_dword v2, v1, s[4:5] sc1
	s_mov_b64 s[10:11], -1
	s_waitcnt vmcnt(0)
	v_cmp_lt_u32_e32 vcc, s101, v2
	s_cbranch_vccnz .LBB0_598
	s_cmp_lg_u32 s0, 0
	s_sleep 1
	s_cbranch_scc0 .LBB0_597
	global_load_dword v2, v1, s[4:5] sc1
	s_waitcnt vmcnt(0)
	v_cmp_ge_u32_e32 vcc, s101, v2
	s_cbranch_vccz .LBB0_598
	s_sleep 1
	global_load_dword v2, v1, s[4:5] sc1
	s_waitcnt vmcnt(0)
	v_cmp_ge_u32_e32 vcc, s101, v2
	s_cbranch_vccz .LBB0_598
	s_sleep 1
	global_load_dword v2, v1, s[4:5] sc1
	s_waitcnt vmcnt(0)
	v_cmp_ge_u32_e32 vcc, s101, v2
	s_cbranch_vccz .LBB0_598
	s_sleep 1
	global_load_dword v2, v1, s[4:5] sc1
	s_waitcnt vmcnt(0)
	v_cmp_ge_u32_e32 vcc, s101, v2
	s_cbranch_vccz .LBB0_598
	s_sleep 1
	global_load_dword v2, v1, s[4:5] sc1
	s_waitcnt vmcnt(0)
	v_cmp_ge_u32_e32 vcc, s101, v2
	s_cbranch_vccz .LBB0_598
	s_sleep 1
	global_load_dword v2, v1, s[4:5] sc1
	s_waitcnt vmcnt(0)
	v_cmp_ge_u32_e32 vcc, s101, v2
	s_cbranch_vccz .LBB0_598
	s_sleep 1
	global_load_dword v2, v1, s[4:5] sc1
	s_waitcnt vmcnt(0)
	v_cmp_ge_u32_e32 vcc, s101, v2
	s_cbranch_vccz .LBB0_598
	s_sleep 1
	s_add_i32 s0, s0, -8
	s_mov_b64 s[10:11], 0
	s_branch .LBB0_598
